# split grid barrier: arrive at step tail, wait (poll + exit s_barrier) moved behind the next step's scalar decode; L1 invalidate on wave 1
# speedup vs baseline: 1.0072x; 1.0072x over previous
; #define LAS __attribute__((address_space(3)))
; __device__ __forceinline__ unsigned xb_ld(unsigned* p)              { return __hip_atomic_load(p, __ATOMIC_RELAXED, __HIP_MEMORY_SCOPE_AGENT); }
; __device__ __forceinline__ unsigned xb_add(unsigned* p, unsigned v) { return __hip_atomic_fetch_add(p, v, __ATOMIC_RELAXED, __HIP_MEMORY_SCOPE_AGENT); }
; __device__ __forceinline__ unsigned xb_xcc_id() { return (unsigned)__builtin_amdgcn_s_getreg((3 << 11) | 20) & 0xFu; }
; __device__ __forceinline__ XcdBarrier xcd_barrier_post(unsigned* bar, volatile LAS unsigned* st, int wave0) {
;     XcdBarrier b; b.bar = bar; b.x = xb_xcc_id(); b.st = st; b.wave0 = wave0;
;     if (tid_of(wave0) == 0) { st[2] = xb_ld(&bar[XB_TOP]); (void)xb_add(&bar[XB_XCNT(b.x)], 1u); }
;     return b;
; __global__ void __launch_bounds__(NTHR, 2) dit_fwd(Args args) {
;     ...
;     const int wave0 = __builtin_amdgcn_readfirstlane(threadIdx.x >> 6);
;     for (int u = tid_of(wave0); u < (LDS_BYTES - LDSCTL_OFF) / 4; u += NTHR) ((LAS unsigned*)(lds + LDSCTL_OFF))[u] = 0u;
;     __syncthreads();
;     XcdBarrier bar; bar.bar = (unsigned*)(args.ws + WS_CTL) + CW_BAR; bar.x = 0; bar.st = nullptr; bar.wave0 = wave0;
;     if (!MK_PER_PHASE) bar = xcd_barrier_post((unsigned*)(args.ws + WS_CTL) + CW_BAR, (volatile LAS unsigned*)(lds + MISC_OFF) + 8, wave0);
.LBB0_3:
	s_or_b64 exec, exec, s[2:3]
	s_load_dwordx16 s[56:71], s[0:1], 0x0
	s_load_dwordx16 s[8:23], s[0:1], 0x40
	s_load_dwordx8 s[80:87], s[0:1], 0x80
	s_waitcnt lgkmcnt(0)
	s_mov_b32 s100, 0
	s_mov_b32 s101, 0
	s_barrier
	v_writelane_b32 v253, s8, 37
	s_getreg_b32 s2, hwreg(HW_REG_XCC_ID, 0, 4)
	s_nop 0
	v_writelane_b32 v253, s9, 38
	v_writelane_b32 v253, s10, 39
	v_writelane_b32 v253, s11, 40
	v_writelane_b32 v253, s12, 41
	v_writelane_b32 v253, s13, 42
	v_writelane_b32 v253, s14, 43
	v_writelane_b32 v253, s15, 44
	v_writelane_b32 v253, s16, 45
	v_writelane_b32 v253, s17, 46
	v_writelane_b32 v253, s18, 47
	v_writelane_b32 v253, s19, 48
	v_writelane_b32 v253, s20, 49
	v_writelane_b32 v253, s21, 50
	v_writelane_b32 v253, s22, 51
	v_writelane_b32 v253, s23, 52
	v_writelane_b32 v253, s80, 53
	s_add_u32 s92, s86, 0x4000
	s_addc_u32 s93, s87, 0
	v_writelane_b32 v253, s81, 54
	v_writelane_b32 v253, s82, 55
	v_writelane_b32 v253, s83, 56
	v_writelane_b32 v253, s84, 57
	s_and_b32 s4, s2, 15
	s_mov_b32 s2, -1
	v_writelane_b32 v253, s85, 58
	s_lshl_b32 s3, s5, 6
	v_mbcnt_lo_u32_b32 v0, s2, 0
	v_writelane_b32 v253, s86, 59
	s_sub_i32 s95, 0, s3
	v_mbcnt_hi_u32_b32 v0, s2, v0
	v_writelane_b32 v253, s87, 60
	v_cmp_eq_u32_e32 vcc, s95, v0
	s_and_saveexec_b64 s[2:3], vcc
	s_cbranch_execz .LBB0_6
	v_mov_b32_e32 v0, 0x7000
	global_load_dword v0, v0, s[86:87] offset:1024 sc1
	s_mov_b64 s[8:9], exec
	v_mbcnt_lo_u32_b32 v2, s8, 0
	v_mbcnt_hi_u32_b32 v2, s9, v2
	s_add_i32 s5, 0, 0x20168
	v_cmp_eq_u32_e32 vcc, 0, v2
	v_mov_b32_e32 v1, s5
	s_and_b64 s[6:7], exec, vcc
	s_waitcnt vmcnt(0)
	ds_write_b32 v1, v0
	s_mov_b64 exec, s[6:7]
	s_cbranch_execz .LBB0_6
	s_lshl_b32 s5, s4, 8
	s_bcnt1_i32_b64 s6, s[8:9]
	v_mov_b32_e32 v0, s5
	v_mov_b32_e32 v1, s6
	global_atomic_add v0, v1, s[92:93] offset:1024

; __device__ __forceinline__ unsigned xb_ld(unsigned* p)              { return __hip_atomic_load(p, __ATOMIC_RELAXED, __HIP_MEMORY_SCOPE_AGENT); }
; __device__ __forceinline__ unsigned xb_add(unsigned* p, unsigned v) { return __hip_atomic_fetch_add(p, v, __ATOMIC_RELAXED, __HIP_MEMORY_SCOPE_AGENT); }
; #define XB_SPIN(cond, bar) do { unsigned _sp = 0; while (cond) { __builtin_amdgcn_s_sleep(1); \
;     if ((++_sp & 255u) == 0u) { if (xb_ld(&(bar)[XB_TMO])) break; if (_sp > XB_SPIN_CAP) { atomicAdd(&(bar)[XB_TMO], 1u); break; } } } } while (0)
; __device__ __forceinline__ void xcd_barrier(const XcdBarrier& b) {
;     ...
;         const unsigned target = b.st[2] + nx;
;         __builtin_amdgcn_fence(__ATOMIC_ACQUIRE, "agent");
;         const unsigned old = xb_add(&bar[XB_XSUB(b.x)], 1u);
;         const unsigned gen = old / nloc;
;         if (old + 1u == (gen + 1u) * nloc) {
;             __builtin_amdgcn_fence(__ATOMIC_RELEASE, "agent");
;             asm volatile("s_waitcnt vmcnt(0)" ::: "memory");
;             (void)xb_add(&bar[XB_TOP], 1u);
;         }
;         XB_SPIN((int)(xb_ld(&bar[XB_TOP]) - target) < 0, bar);
;         asm volatile("s_waitcnt vmcnt(0)" ::: "memory");
;         b.st[2] = target;
;     }
;     __syncthreads();
.LBB0_8:
	s_or_b64 exec, exec, s[16:17]
	v_readlane_b32 s4, v253, 29
	v_readfirstlane_b32 s101, v0
	s_nop 1
	v_mov_b32_e32 v1, s4
	ds_write_b32 v1, v0
.LBB0_9:
	s_or_b64 exec, exec, s[2:3]
	s_waitcnt lgkmcnt(0)

; __device__ __forceinline__ unsigned xb_ld(unsigned* p)              { return __hip_atomic_load(p, __ATOMIC_RELAXED, __HIP_MEMORY_SCOPE_AGENT); }
; #define XB_SPIN(cond, bar) do { unsigned _sp = 0; while (cond) { __builtin_amdgcn_s_sleep(1); \
;     if ((++_sp & 255u) == 0u) { if (xb_ld(&(bar)[XB_TMO])) break; if (_sp > XB_SPIN_CAP) { atomicAdd(&(bar)[XB_TMO], 1u); break; } } } } while (0)
; __device__ __forceinline__ void xcd_barrier(const XcdBarrier& b) {
;     ...
;         XB_SPIN((int)(xb_ld(&bar[XB_TOP]) - target) < 0, bar);
;         asm volatile("s_waitcnt vmcnt(0)" ::: "memory");
;         b.st[2] = target;
;     }
;     __syncthreads();
; __device__ __forceinline__ void ffn_fixup(const Args& a, int layer, int nrows, int gt, int NT) {
;     typedef _Float16 sh4 __attribute__((ext_vector_type(4)));
;     const _Float16* SIDE = (const _Float16*)(a.ws + WS_SIDE); bf16_t* ACT = (bf16_t*)(a.ws + WS_BIG); const float* cw = a.in[16] + (size_t)layer * 3 * DFF;
;     const int nblk = nrows >> 6;
;     for (int idx = gt; idx < nblk * 2 * (DFF / 4); idx += NT) {
;         const int c4 = idx % (DFF / 4), bw = idx / (DFF / 4), blk = bw >> 1, which = bw & 1, col = 4 * c4;
.LBB0_104:
	s_cmp_eq_u32 s100, 0
	s_cbranch_scc1 .Lp1_skip
	s_mov_b32 s100, 0
	s_cmp_lg_u32 s95, 0
	s_cbranch_scc1 .Lp1_all
	s_mov_b64 s[0:1], exec
	s_mov_b64 exec, 1
	v_mov_b32_e32 v250, 0x3400
	v_mov_b32_e32 v251, 0
	s_mov_b32 vcc_hi, 0
	v_lshl_add_u64 v[248:249], s[92:93], 0, v[250:251]
.Lp1_poll:
	global_load_dword v250, v[248:249], off sc1
	s_waitcnt vmcnt(0)
	v_readfirstlane_b32 vcc_lo, v250
	s_sub_i32 vcc_lo, vcc_lo, s101
	s_cmp_lt_i32 vcc_lo, 0
	s_cbranch_scc0 .Lp1_done
	s_sleep 1
	s_add_i32 vcc_hi, vcc_hi, 1
	s_cmp_lt_u32 vcc_hi, 0x40000
	s_cbranch_scc1 .Lp1_poll
.Lp1_done:
	s_mov_b64 exec, s[0:1]
.Lp1_all:
	s_waitcnt vmcnt(0) lgkmcnt(0)
	s_barrier
.Lp1_skip:
	s_nop 0
	v_readlane_b32 s0, v254, 32
	v_readlane_b32 s1, v254, 33
	s_xor_b64 s[0:1], s[0:1], -1
	v_writelane_b32 v254, s0, 47
	v_and_b32_e32 v240, 63, v204
	s_nop 0
	v_writelane_b32 v254, s1, 48
	s_ashr_i32 s0, s4, 6
	v_writelane_b32 v254, s0, 49
	s_nop 0
	v_readlane_b32 s0, v254, 14
	s_cmp_lt_i32 s0, 4
	s_mov_b64 s[0:1], -1
	s_cbranch_scc1 .LBB0_249
	v_readlane_b32 s0, v254, 14
	s_cmp_lt_i32 s0, 5
	s_mov_b64 s[0:1], -1
	s_cbranch_scc1 .LBB0_144
	v_readlane_b32 s0, v254, 14
	s_cmp_gt_i32 s0, 5
	s_mov_b64 s[0:1], -1
	s_cbranch_scc0 .LBB0_115
	v_readlane_b32 s0, v254, 8
	s_lshr_b32 s5, s0, 5
	v_lshl_add_u32 v8, s26, 9, v204
	s_mulk_i32 s5, 0x2c0
	v_cmp_gt_i32_e32 vcc, s5, v8
	s_and_saveexec_b64 s[0:1], vcc
	s_movk_i32 s20, 0x1600
	s_cbranch_execz .LBB0_114
	s_lshl_b32 s14, s11, 9
	s_mul_i32 s8, s10, 0x8400
	s_mul_hi_i32 s9, s10, 0x8400
	s_add_u32 s8, s80, s8
	s_addc_u32 s9, s81, s9
	s_add_u32 s36, s8, 0x5800
	s_addc_u32 s37, s9, 0
	v_lshlrev_b32_e32 v9, 2, v8
	s_lshl_b32 s16, s11, 11
	s_mov_b64 s[38:39], 0
	s_branch .LBB0_110

; __device__ __forceinline__ void xcd_barrier(const XcdBarrier& b) {
;     asm volatile("s_waitcnt vmcnt(0)" ::: "memory");
;     __syncthreads();
;     if (tid_of(b.wave0) == 0) {
.LBB0_773:
	s_mov_b32 s2, -1
	s_waitcnt vmcnt(0)
	s_waitcnt vmcnt(0) lgkmcnt(0)
	s_barrier
	s_mov_b32 s100, 1
	s_cmp_lg_u32 s95, 0xffffffc0
	s_cbranch_scc1 .Lp1_notw1
	buffer_inv sc1

; __device__ __forceinline__ unsigned xb_ld(unsigned* p)              { return __hip_atomic_load(p, __ATOMIC_RELAXED, __HIP_MEMORY_SCOPE_AGENT); }
; __device__ __forceinline__ unsigned xb_add(unsigned* p, unsigned v) { return __hip_atomic_fetch_add(p, v, __ATOMIC_RELAXED, __HIP_MEMORY_SCOPE_AGENT); }
; #define XB_SPIN(cond, bar) do { unsigned _sp = 0; while (cond) { __builtin_amdgcn_s_sleep(1); \
;     if ((++_sp & 255u) == 0u) { if (xb_ld(&(bar)[XB_TMO])) break; if (_sp > XB_SPIN_CAP) { atomicAdd(&(bar)[XB_TMO], 1u); break; } } } } while (0)
; __device__ __forceinline__ void xcd_barrier(const XcdBarrier& b) {
;     ...
;         const unsigned target = b.st[2] + nx;
;         __builtin_amdgcn_fence(__ATOMIC_ACQUIRE, "agent");
;         const unsigned old = xb_add(&bar[XB_XSUB(b.x)], 1u);
;         const unsigned gen = old / nloc;
;         if (old + 1u == (gen + 1u) * nloc) {
;             __builtin_amdgcn_fence(__ATOMIC_RELEASE, "agent");
;             asm volatile("s_waitcnt vmcnt(0)" ::: "memory");
;             (void)xb_add(&bar[XB_TOP], 1u);
;         }
;         XB_SPIN((int)(xb_ld(&bar[XB_TOP]) - target) < 0, bar);
.LBB0_788:
	v_readlane_b32 s4, v253, 29
	s_nop 1
	v_mov_b32_e32 v2, s4
	v_readlane_b32 s4, v253, 24
	s_add_u32 s4, s8, s4
	s_addc_u32 s5, s9, 0
	v_mov_b32_e32 v3, s4
	v_add_co_u32_e32 v4, vcc, 0x1000, v3
	v_mov_b32_e32 v3, s5
	s_nop 0
	v_addc_co_u32_e32 v5, vcc, 0, v3, vcc
	ds_read_b32 v2, v2
	s_waitcnt vmcnt(0) lgkmcnt(0)
	flat_atomic_add v3, v[4:5], v226 offset:1024 sc0
	v_cvt_f32_u32_e32 v4, v0
	v_sub_u32_e32 v5, 0, v0
	v_rcp_iflag_f32_e32 v4, v4
	s_nop 0
	v_mul_f32_e32 v4, 0x4f7ffffe, v4
	v_cvt_u32_f32_e32 v4, v4
	v_mul_lo_u32 v5, v5, v4
	v_mul_hi_u32 v5, v4, v5
	v_add_u32_e32 v4, v4, v5
	s_waitcnt vmcnt(0) lgkmcnt(0)
	v_mul_hi_u32 v4, v3, v4
	v_mul_lo_u32 v5, v4, v0
	v_sub_u32_e32 v5, v3, v5
	v_cmp_ge_u32_e32 vcc, v5, v0
	v_add_u32_e32 v6, 1, v4
	v_add_u32_e32 v3, 1, v3
	v_cndmask_b32_e32 v4, v4, v6, vcc
	v_sub_u32_e32 v6, v5, v0
	v_cndmask_b32_e32 v5, v5, v6, vcc
	v_cmp_ge_u32_e32 vcc, v5, v0
	v_add_u32_e32 v5, 1, v4
	s_nop 0
	v_cndmask_b32_e32 v4, v4, v5, vcc
	v_mad_u64_u32 v[4:5], s[4:5], v0, v4, v[0:1]
	v_cmp_eq_u32_e32 vcc, v3, v4
	s_and_saveexec_b64 s[12:13], vcc
	s_cbranch_execz .LBB0_790
	v_mov_b32_e32 v0, s8
	v_add_co_u32_e32 v4, vcc, 0x3000, v0
	v_mov_b32_e32 v0, s9
	buffer_wbl2 sc1
	s_waitcnt vmcnt(0)
	v_addc_co_u32_e32 v5, vcc, 0, v0, vcc
	flat_atomic_add v[4:5], v226 offset:1024
.LBB0_790:
	s_or_b64 exec, exec, s[12:13]
	v_add_u32_e32 v0, v2, v1
	s_mov_b64 s[16:17], 0
	s_getpc_b64 s[98:99]
